# adds: top-k threshold search counts keys with 2 VALU per key (rotating SGPR mask pairs) instead of 3 / 4.5
# speedup vs baseline: 1.0076x; 1.0076x over previous
.LBB0_1185:
	v_mul_f32_e32 v163, 0.5, v96
	v_fmac_f32_e32 v163, 0.5, v97
	s_nop 0
	v_readfirstlane_b32 s0, v163
	s_not_b32 s1, s0
	s_or_b32 s5, s0, 0x80000000
	s_cmp_lt_i32 s0, 0
	s_cselect_b32 s15, s1, s5
	s_cmp_gt_u32 s15, s10
	s_cselect_b64 s[0:1], -1, 0
	s_cmp_lt_u32 s15, s12
	s_cselect_b64 s[8:9], -1, 0
	s_lshr_b32 s14, s4, 1
	s_and_b64 s[0:1], s[0:1], s[8:9]
	s_add_i32 s14, s14, s10
	s_and_b64 s[4:5], s[0:1], exec
	s_cselect_b32 s15, s15, s14
	v_mov_b32_e32 v164, 0
	v_mov_b32_e32 v165, 0
	v_cmp_le_u32_e32 vcc, s15, v124
	v_cmp_le_u32_e64 s[98:99], s15, v161
	v_cmp_le_u32_e64 s[100:101], s15, v122
	v_addc_co_u32_e32 v164, vcc, 0, v164, vcc
	v_cmp_le_u32_e32 vcc, s15, v127
	v_addc_co_u32_e64 v165, s[98:99], 0, v165, s[98:99]
	v_cmp_le_u32_e64 s[98:99], s15, v118
	v_addc_co_u32_e64 v164, s[100:101], 0, v164, s[100:101]
	v_cmp_le_u32_e64 s[100:101], s15, v121
	v_addc_co_u32_e32 v165, vcc, 0, v165, vcc
	v_cmp_le_u32_e32 vcc, s15, v114
	v_addc_co_u32_e64 v164, s[98:99], 0, v164, s[98:99]
	v_cmp_le_u32_e64 s[98:99], s15, v115
	v_addc_co_u32_e64 v165, s[100:101], 0, v165, s[100:101]
	v_cmp_le_u32_e64 s[100:101], s15, v119
	v_addc_co_u32_e32 v164, vcc, 0, v164, vcc
	v_cmp_le_u32_e32 vcc, s15, v123
	v_addc_co_u32_e64 v165, s[98:99], 0, v165, s[98:99]
	v_cmp_le_u32_e64 s[98:99], s15, v108
	v_addc_co_u32_e64 v164, s[100:101], 0, v164, s[100:101]
	v_cmp_le_u32_e64 s[100:101], s15, v109
	v_addc_co_u32_e32 v165, vcc, 0, v165, vcc
	v_cmp_le_u32_e32 vcc, s15, v104
	v_addc_co_u32_e64 v164, s[98:99], 0, v164, s[98:99]
	v_cmp_le_u32_e64 s[98:99], s15, v105
	v_addc_co_u32_e64 v165, s[100:101], 0, v165, s[100:101]
	v_cmp_le_u32_e64 s[100:101], s15, v99
	v_addc_co_u32_e32 v164, vcc, 0, v164, vcc
	v_cmp_le_u32_e32 vcc, s15, v101
	v_addc_co_u32_e64 v165, s[98:99], 0, v165, s[98:99]
	v_cmp_le_u32_e64 s[98:99], s15, v162
	v_addc_co_u32_e64 v164, s[100:101], 0, v164, s[100:101]
	v_cmp_le_u32_e64 s[100:101], s15, v125
	v_addc_co_u32_e32 v165, vcc, 0, v165, vcc
	v_cmp_le_u32_e32 vcc, s15, v117
	v_addc_co_u32_e64 v164, s[98:99], 0, v164, s[98:99]
	v_cmp_le_u32_e64 s[98:99], s15, v111
	v_addc_co_u32_e64 v165, s[100:101], 0, v165, s[100:101]
	v_cmp_le_u32_e64 s[100:101], s15, v113
	v_addc_co_u32_e32 v164, vcc, 0, v164, vcc
	v_cmp_le_u32_e32 vcc, s15, v107
	v_addc_co_u32_e64 v165, s[98:99], 0, v165, s[98:99]
	v_cmp_le_u32_e64 s[98:99], s15, v103
	v_addc_co_u32_e64 v164, s[100:101], 0, v164, s[100:101]
	v_cmp_le_u32_e64 s[100:101], s15, v100
	v_addc_co_u32_e32 v165, vcc, 0, v165, vcc
	v_cmp_le_u32_e32 vcc, s15, v126
	v_addc_co_u32_e64 v164, s[98:99], 0, v164, s[98:99]
	v_cmp_le_u32_e64 s[98:99], s15, v120
	v_addc_co_u32_e64 v165, s[100:101], 0, v165, s[100:101]
	v_cmp_le_u32_e64 s[100:101], s15, v116
	v_addc_co_u32_e32 v164, vcc, 0, v164, vcc
	v_cmp_le_u32_e32 vcc, s15, v110
	v_addc_co_u32_e64 v165, s[98:99], 0, v165, s[98:99]
	v_cmp_le_u32_e64 s[98:99], s15, v112
	v_addc_co_u32_e64 v164, s[100:101], 0, v164, s[100:101]
	v_cmp_le_u32_e64 s[100:101], s15, v106
	v_addc_co_u32_e32 v165, vcc, 0, v165, vcc
	v_cmp_le_u32_e32 vcc, s15, v102
	v_addc_co_u32_e64 v164, s[98:99], 0, v164, s[98:99]
	v_cmp_le_u32_e64 s[98:99], s15, v98
	v_addc_co_u32_e64 v165, s[100:101], 0, v165, s[100:101]
	v_addc_co_u32_e32 v164, vcc, 0, v164, vcc
	v_addc_co_u32_e64 v165, s[98:99], 0, v165, s[98:99]
	v_add_u32_e32 v164, v164, v165
	s_nop 1
	v_add_u32_dpp v164, v164, v164 quad_perm:[1,0,3,2] row_mask:0xf bank_mask:0xf bound_ctrl:1
	s_nop 1
	v_add_u32_dpp v164, v164, v164 quad_perm:[2,3,0,1] row_mask:0xf bank_mask:0xf bound_ctrl:1
	s_nop 1
	v_add_u32_dpp v164, v164, v164 row_half_mirror row_mask:0xf bank_mask:0xf bound_ctrl:1
	s_nop 1
	v_add_u32_dpp v164, v164, v164 row_mirror row_mask:0xf bank_mask:0xf bound_ctrl:1
	s_nop 0
	v_readlane_b32 s4, v164, 0
	v_readlane_b32 s5, v164, 16
	s_add_i32 s4, s5, s4
	v_readlane_b32 s5, v164, 32
	s_add_i32 s4, s4, s5
	v_readlane_b32 s5, v164, 48
	s_add_i32 s21, s4, s5
	s_cmpk_gt_i32 s21, 0xff
	s_cselect_b64 s[4:5], -1, 0
	s_and_b64 s[8:9], s[4:5], exec
	s_cselect_b32 s13, s21, s13
	s_cselect_b32 s11, s11, s21
	s_cselect_b32 s12, s12, s15
	s_cselect_b32 s10, s15, s10
	s_cmpk_eq_i32 s21, 0x100
	s_cselect_b64 s[8:9], -1, 0
	s_sub_i32 s15, s13, s11
	s_cmpk_lt_i32 s15, 0x41
	s_cselect_b64 s[22:23], -1, 0
	s_or_b64 s[22:23], s[8:9], s[22:23]
	s_andn2_b64 vcc, exec, s[22:23]
	s_cbranch_vccnz .LBB0_1184

.LBB0_1346:
	v_mul_f32_e32 v98, 0.5, v96
	v_fmac_f32_e32 v98, 0.5, v97
	s_nop 0
	v_readfirstlane_b32 s0, v98
	s_not_b32 s1, s0
	s_or_b32 s4, s0, 0x80000000
	s_cmp_lt_i32 s0, 0
	s_cselect_b32 s6, s1, s4
	s_cmp_gt_u32 s6, s8
	s_cselect_b64 s[0:1], -1, 0
	s_cmp_lt_u32 s6, s9
	s_cselect_b64 s[4:5], -1, 0
	s_lshr_b32 s11, s11, 1
	s_and_b64 s[4:5], s[0:1], s[4:5]
	s_add_i32 s11, s11, s8
	s_and_b64 s[0:1], s[4:5], exec
	s_cselect_b32 s12, s6, s11
	v_mov_b32_e32 v99, 0
	v_mov_b32_e32 v100, 0
	v_cmp_le_u32_e32 vcc, s12, v2
	v_cmp_le_u32_e64 s[98:99], s12, v3
	v_cmp_le_u32_e64 s[100:101], s12, v1
	v_addc_co_u32_e32 v99, vcc, 0, v99, vcc
	v_cmp_le_u32_e32 vcc, s12, v0
	v_addc_co_u32_e64 v100, s[98:99], 0, v100, s[98:99]
	v_cmp_le_u32_e64 s[98:99], s12, v6
	v_addc_co_u32_e64 v99, s[100:101], 0, v99, s[100:101]
	v_cmp_le_u32_e64 s[100:101], s12, v7
	v_addc_co_u32_e32 v100, vcc, 0, v100, vcc
	v_cmp_le_u32_e32 vcc, s12, v5
	v_addc_co_u32_e64 v99, s[98:99], 0, v99, s[98:99]
	v_cmp_le_u32_e64 s[98:99], s12, v4
	v_addc_co_u32_e64 v100, s[100:101], 0, v100, s[100:101]
	v_cmp_le_u32_e64 s[100:101], s12, v9
	v_addc_co_u32_e32 v99, vcc, 0, v99, vcc
	v_cmp_le_u32_e32 vcc, s12, v8
	v_addc_co_u32_e64 v100, s[98:99], 0, v100, s[98:99]
	v_cmp_le_u32_e64 s[98:99], s12, v10
	v_addc_co_u32_e64 v99, s[100:101], 0, v99, s[100:101]
	v_cmp_le_u32_e64 s[100:101], s12, v11
	v_addc_co_u32_e32 v100, vcc, 0, v100, vcc
	v_cmp_le_u32_e32 vcc, s12, v14
	v_addc_co_u32_e64 v99, s[98:99], 0, v99, s[98:99]
	v_cmp_le_u32_e64 s[98:99], s12, v15
	v_addc_co_u32_e64 v100, s[100:101], 0, v100, s[100:101]
	v_cmp_le_u32_e64 s[100:101], s12, v13
	v_addc_co_u32_e32 v99, vcc, 0, v99, vcc
	v_cmp_le_u32_e32 vcc, s12, v12
	v_addc_co_u32_e64 v100, s[98:99], 0, v100, s[98:99]
	v_cmp_le_u32_e64 s[98:99], s12, v18
	v_addc_co_u32_e64 v99, s[100:101], 0, v99, s[100:101]
	v_cmp_le_u32_e64 s[100:101], s12, v19
	v_addc_co_u32_e32 v100, vcc, 0, v100, vcc
	v_cmp_le_u32_e32 vcc, s12, v17
	v_addc_co_u32_e64 v99, s[98:99], 0, v99, s[98:99]
	v_cmp_le_u32_e64 s[98:99], s12, v16
	v_addc_co_u32_e64 v100, s[100:101], 0, v100, s[100:101]
	v_cmp_le_u32_e64 s[100:101], s12, v22
	v_addc_co_u32_e32 v99, vcc, 0, v99, vcc
	v_cmp_le_u32_e32 vcc, s12, v23
	v_addc_co_u32_e64 v100, s[98:99], 0, v100, s[98:99]
	v_cmp_le_u32_e64 s[98:99], s12, v21
	v_addc_co_u32_e64 v99, s[100:101], 0, v99, s[100:101]
	v_cmp_le_u32_e64 s[100:101], s12, v20
	v_addc_co_u32_e32 v100, vcc, 0, v100, vcc
	v_cmp_le_u32_e32 vcc, s12, v25
	v_addc_co_u32_e64 v99, s[98:99], 0, v99, s[98:99]
	v_cmp_le_u32_e64 s[98:99], s12, v24
	v_addc_co_u32_e64 v100, s[100:101], 0, v100, s[100:101]
	v_cmp_le_u32_e64 s[100:101], s12, v26
	v_addc_co_u32_e32 v99, vcc, 0, v99, vcc
	v_cmp_le_u32_e32 vcc, s12, v27
	v_addc_co_u32_e64 v100, s[98:99], 0, v100, s[98:99]
	v_cmp_le_u32_e64 s[98:99], s12, v30
	v_addc_co_u32_e64 v99, s[100:101], 0, v99, s[100:101]
	v_cmp_le_u32_e64 s[100:101], s12, v31
	v_addc_co_u32_e32 v100, vcc, 0, v100, vcc
	v_cmp_le_u32_e32 vcc, s12, v29
	v_addc_co_u32_e64 v99, s[98:99], 0, v99, s[98:99]
	v_cmp_le_u32_e64 s[98:99], s12, v28
	v_addc_co_u32_e64 v100, s[100:101], 0, v100, s[100:101]
	v_addc_co_u32_e32 v99, vcc, 0, v99, vcc
	v_addc_co_u32_e64 v100, s[98:99], 0, v100, s[98:99]
	v_add_u32_e32 v99, v99, v100
	s_nop 1
	v_add_u32_dpp v99, v99, v99 quad_perm:[1,0,3,2] row_mask:0xf bank_mask:0xf bound_ctrl:1
	s_nop 1
	v_add_u32_dpp v99, v99, v99 quad_perm:[2,3,0,1] row_mask:0xf bank_mask:0xf bound_ctrl:1
	s_nop 1
	v_add_u32_dpp v99, v99, v99 row_half_mirror row_mask:0xf bank_mask:0xf bound_ctrl:1
	s_nop 1
	v_add_u32_dpp v99, v99, v99 row_mirror row_mask:0xf bank_mask:0xf bound_ctrl:1
	s_nop 0
	v_readlane_b32 s0, v99, 0
	v_readlane_b32 s1, v99, 16
	v_readlane_b32 s6, v99, 32
	s_add_i32 s0, s1, s0
	v_readlane_b32 s7, v99, 48
	s_add_i32 s0, s0, s6
	s_add_i32 s13, s0, s7
	s_cmpk_gt_i32 s13, 0xff
	s_cselect_b64 s[0:1], -1, 0
	s_and_b64 s[6:7], s[0:1], exec
	s_cselect_b32 s10, s13, s10
	s_cselect_b32 s21, s21, s13
	s_cselect_b32 s9, s9, s12
	s_cselect_b32 s8, s12, s8
	s_cmpk_eq_i32 s13, 0x100
	s_cselect_b64 s[6:7], -1, 0
	s_sub_i32 s12, s10, s21
	s_cmpk_lt_i32 s12, 0x41
	s_cselect_b64 s[14:15], -1, 0
	s_or_b64 s[14:15], s[6:7], s[14:15]
	s_andn2_b64 vcc, exec, s[14:15]
	s_cbranch_vccnz .LBB0_1345

	.amdhsa_kernel _Z10fwd_kernel4Args
		.amdhsa_group_segment_fixed_size 0
		.amdhsa_private_segment_fixed_size 0
		.amdhsa_kernarg_size 408
		.amdhsa_user_sgpr_count 2
		.amdhsa_user_sgpr_dispatch_ptr 0
		.amdhsa_user_sgpr_queue_ptr 0
		.amdhsa_user_sgpr_kernarg_segment_ptr 1
		.amdhsa_user_sgpr_dispatch_id 0
		.amdhsa_user_sgpr_kernarg_preload_length 0
		.amdhsa_user_sgpr_kernarg_preload_offset 0
		.amdhsa_user_sgpr_private_segment_size 0
		.amdhsa_uses_dynamic_stack 0
		.amdhsa_enable_private_segment 0
		.amdhsa_system_sgpr_workgroup_id_x 1
		.amdhsa_system_sgpr_workgroup_id_y 0
		.amdhsa_system_sgpr_workgroup_id_z 0
		.amdhsa_system_sgpr_workgroup_info 0
		.amdhsa_system_vgpr_workitem_id 2
		.amdhsa_next_free_vgpr 256
		.amdhsa_next_free_sgpr 102
		.amdhsa_accum_offset 256
		.amdhsa_reserve_vcc 1
		.amdhsa_float_round_mode_32 0
		.amdhsa_float_round_mode_16_64 0
		.amdhsa_float_denorm_mode_32 3
		.amdhsa_float_denorm_mode_16_64 3
		.amdhsa_dx10_clamp 1
		.amdhsa_ieee_mode 1
		.amdhsa_fp16_overflow 0
		.amdhsa_tg_split 0
		.amdhsa_exception_fp_ieee_invalid_op 0
		.amdhsa_exception_fp_denorm_src 0
		.amdhsa_exception_fp_ieee_div_zero 0
		.amdhsa_exception_fp_ieee_overflow 0
		.amdhsa_exception_fp_ieee_underflow 0
		.amdhsa_exception_fp_ieee_inexact 0
		.amdhsa_exception_int_div_zero 0
	.end_amdhsa_kernel

amdhsa.kernels:
  - .agpr_count:     0
    .args:
      - .offset:         0
        .size:           152
        .value_kind:     by_value
      - .offset:         152
        .size:           4
        .value_kind:     hidden_block_count_x
      - .offset:         156
        .size:           4
        .value_kind:     hidden_block_count_y
      - .offset:         160
        .size:           4
        .value_kind:     hidden_block_count_z
      - .offset:         164
        .size:           2
        .value_kind:     hidden_group_size_x
      - .offset:         166
        .size:           2
        .value_kind:     hidden_group_size_y
      - .offset:         168
        .size:           2
        .value_kind:     hidden_group_size_z
      - .offset:         170
        .size:           2
        .value_kind:     hidden_remainder_x
      - .offset:         172
        .size:           2
        .value_kind:     hidden_remainder_y
      - .offset:         174
        .size:           2
        .value_kind:     hidden_remainder_z
      - .offset:         192
        .size:           8
        .value_kind:     hidden_global_offset_x
      - .offset:         200
        .size:           8
        .value_kind:     hidden_global_offset_y
      - .offset:         208
        .size:           8
        .value_kind:     hidden_global_offset_z
      - .offset:         216
        .size:           2
        .value_kind:     hidden_grid_dims
      - .offset:         240
        .size:           8
        .value_kind:     hidden_multigrid_sync_arg
      - .offset:         272
        .size:           4
        .value_kind:     hidden_dynamic_lds_size
    .group_segment_fixed_size: 0
    .kernarg_segment_align: 8
    .kernarg_segment_size: 408
    .language:       OpenCL C
    .language_version:
      - 2
      - 0
    .max_flat_workgroup_size: 512
    .name:           _Z10fwd_kernel4Args
    .private_segment_fixed_size: 0
    .sgpr_count:     108
    .sgpr_spill_count: 26
    .symbol:         _Z10fwd_kernel4Args.kd
    .uniform_work_group_size: 1
    .uses_dynamic_stack: false
    .vgpr_count:     256
    .vgpr_spill_count: 0
    .wavefront_size: 64
